# B q/k epilogue: rope cos/sin table (16 KB) L1-warmed by 2 dummy loads per wave before the first rope block
# speedup vs baseline: 1.0045x; 1.0045x over previous
;     __device__ __forceinline__ void operator()(const f32x4 (&acc)[2][2][4][2], const pg8::Unit& u, int wr, int wc, int fr, int fq) const {
;     ...
;                 for (int m = 0; m < 4; ++m) { const int t = t0 + ai * 128 + m * 16; const int pos = isctx ? SEQ + t : t;
;                     f32x4 cs = (f32x4){1.f, 1.f, 1.f, 1.f}, sn = (f32x4){0.f, 0.f, 0.f, 0.f};
;                     if (!isctx) { const int pa = axis ? (t & 63) : (t >> 6); cs = *(const f32x4*)(rope + pa * 16 + 4 * fq); sn = *(const f32x4*)(rope + 2048 + pa * 16 + 4 * fq); }
.LBB0_379:
	s_andn2_b64 vcc, exec, s[34:35]
	s_cbranch_vccnz .LBB0_531
	v_lshlrev_b32_e32 v154, 2, v234
	v_ashrrev_i32_e32 v155, 31, v154
	v_and_b32_e32 v151, 63, v233
	s_and_b64 vcc, exec, s[72:73]
	v_lshlrev_b64 v[152:153], 2, v[154:155]
	s_cbranch_vccz .LBB0_382
	v_readlane_b32 s4, v251, 33
	v_readlane_b32 s5, v251, 34
	v_and_b32_e32 v134, 63, v220
	v_lshlrev_b32_e32 v134, 4, v134
	v_mov_b32_e32 v135, 0
	v_add_u32_e32 v134, s31, v134
	s_nop 3
	v_lshl_add_u64 v[134:135], s[4:5], 0, v[134:135]
	global_load_dword v136, v[134:135], off
	global_load_dword v137, v[134:135], off offset:1024
	v_ashrrev_i32_e32 v96, 6, v150
	v_cndmask_b32_e64 v96, v151, v96, s[38:39]
	v_lshlrev_b32_e32 v130, 4, v96
	v_ashrrev_i32_e32 v131, 31, v130
	v_readlane_b32 s4, v251, 33
	v_lshlrev_b64 v[130:131], 2, v[130:131]
	v_readlane_b32 s5, v251, 34
	s_nop 1
	v_lshl_add_u64 v[132:133], s[4:5], 0, v[130:131]
	v_readlane_b32 s4, v251, 59
	v_readlane_b32 s5, v251, 60
	v_lshl_add_u64 v[132:133], v[132:133], 0, v[152:153]
	s_nop 0
	v_lshl_add_u64 v[130:131], s[4:5], 0, v[130:131]
	v_lshl_add_u64 v[130:131], v[130:131], 0, v[152:153]
	global_load_dwordx4 v[134:137], v[132:133], off
	s_nop 0
	global_load_dwordx4 v[130:133], v[130:131], off
	s_branch .LBB0_383
